# attention key-tile loops: per-tile half-block barrier replaced by a flag barrier (one LDS write + one 16-byte poll instead of hipcc's counter/generation hsync)
# speedup vs baseline: 1.0071x; 1.0071x over previous
; DI int vb_id() { return (int)blockIdx.x + half_id() * (int)gridDim.x; }
; DI int vb_n() { return (int)gridDim.x * 2; }
; DI void phase_prep(const Params& p, char* smem, int part, int vb) {
;     ...
;     const int NITEMS = 1024 + 1024 + 128 + 128 + 256 + 512 + 32;
;     for (int it0 = vb; it0 < NITEMS; it0 += vb_n()) {
;       int it = it0;
;       if (it < 1024) {
;         int row = it * 16 + wave * 4;
;         fp8_rows<4>(p.pu + (size_t)row * 1024, (unsigned char*)(ws + WS_UBF) + (size_t)row * 1024, (float*)(ws + WS_SU) + row, lane);
; __global__ void __launch_bounds__(512) fwd_megakernel(Params p) {
;     ...
;   phase_compress(p, hsm);
;   phase_prep(p, hsm, 1, (vb_id() + vb_n() - 128) % vb_n());
;   xcd_barrier(xb);
;   phase_mix(p, hsm);
.LBB0_529:
	v_writelane_b32 v253, s58, 32
	s_nop 1
	v_writelane_b32 v253, s59, 33
	v_writelane_b32 v253, s72, 34
	s_nop 1
	v_writelane_b32 v253, s73, 35
	v_writelane_b32 v253, s74, 36
	v_writelane_b32 v253, s75, 37
	v_writelane_b32 v253, s76, 38
	v_writelane_b32 v253, s77, 39
	v_writelane_b32 v253, s78, 40
	v_writelane_b32 v253, s79, 41
	v_writelane_b32 v253, s80, 42
	v_writelane_b32 v253, s81, 43
	v_writelane_b32 v253, s82, 44
	v_writelane_b32 v253, s83, 45
	v_writelane_b32 v253, s84, 46
	v_writelane_b32 v253, s85, 47
	v_writelane_b32 v253, s86, 48
	v_writelane_b32 v253, s87, 49
	s_or_b64 exec, exec, s[0:1]
	v_writelane_b32 v253, s60, 50
	v_writelane_b32 v253, s53, 51
	v_writelane_b32 v253, s56, 52
	v_readfirstlane_b32 s0, v211
	s_lshr_b32 s0, s0, 8
	v_writelane_b32 v253, s57, 53
	v_writelane_b32 v253, s54, 54
	s_mul_i32 s0, s0, s54
	s_add_i32 s94, s0, s52
	v_writelane_b32 v253, s55, 55
	s_cmpk_gt_i32 s94, 0x3ff
	s_waitcnt lgkmcnt(0)
	s_barrier
	v_writelane_b32 v253, s52, 56
	v_lshrrev_b32_e32 v250, 8, v211
	v_mul_u32_u24_e32 v250, 0x13f00, v250
	v_add_u32_e32 v250, 0x13ee0, v250
	v_bfe_u32 v249, v211, 6, 2
	v_lshl_add_u32 v249, v249, 2, v250
	v_mov_b32_e32 v251, 0
	ds_write_b32 v249, v251
	s_waitcnt lgkmcnt(0)
	s_barrier
	v_readfirstlane_b32 s0, v211
	s_nop 0
	s_lshr_b32 s0, s0, 8
	s_cmp_lg_u32 s0, 0
	s_cbranch_scc1 .Lp1a_exit
	v_readlane_b32 s74, v253, 36
	v_readlane_b32 s75, v253, 37
	v_readlane_b32 s76, v253, 38
	v_readlane_b32 s77, v253, 39
	v_readlane_b32 s78, v253, 40
	v_readlane_b32 s79, v253, 41
	v_readlane_b32 s80, v253, 42
	v_readlane_b32 s81, v253, 43
	v_readlane_b32 s86, v253, 48
	v_readlane_b32 s87, v253, 49
	s_nop 3
	s_abs_i32 s1, s88
	v_cvt_f32_u32_e32 v0, s1
	v_readfirstlane_b32 s0, v211
	s_lshr_b32 s0, s0, 8
	s_mul_i32 s0, s0, s54
	v_rcp_iflag_f32_e32 v0, v0
	s_add_i32 s2, s52, s88
	s_sub_i32 s4, 0, s1
	s_add_i32 s0, s2, s0
	v_mul_f32_e32 v0, 0x4f7ffffe, v0
	v_cvt_u32_f32_e32 v0, v0
	s_addk_i32 s0, 0xff80
	s_ashr_i32 s2, s0, 31
	s_abs_i32 s0, s0
	v_readfirstlane_b32 s5, v0
	s_mul_i32 s4, s4, s5
	s_mul_hi_u32 s4, s5, s4
	s_add_i32 s5, s5, s4
	s_mul_hi_u32 s4, s0, s5
	s_mul_i32 s4, s4, s1
	s_sub_i32 s0, s0, s4
	s_sub_i32 s4, s0, s1
	s_cmp_ge_u32 s0, s1
	s_cselect_b32 s0, s4, s0
	s_sub_i32 s4, s0, s1
	s_cmp_ge_u32 s0, s1
	s_cselect_b32 s0, s4, s0
	s_xor_b32 s0, s0, s2
	s_sub_i32 s20, s0, s2
	s_mov_b32 s3, 0
	v_mov_b32_e32 v0, v210
	s_cmpk_gt_i32 s20, 0xc1f
	s_cbranch_scc1 .Lp1a_exit
	s_add_u32 s6, s86, 0x1180000
	s_addc_u32 s7, s87, 0
	s_add_u32 s21, s86, 0xd00000
	s_addc_u32 s22, s87, 0
	s_add_u32 s23, s86, 0xb00000
	s_addc_u32 s24, s87, 0
	s_add_u32 s25, s86, 0xa00000
	s_addc_u32 s26, s87, 0
	s_add_u32 s27, s86, 0x900000
	s_addc_u32 s28, s87, 0
	v_and_b32_e32 v2, 63, v0
	s_add_u32 s8, s86, 0x2200204
	v_ashrrev_i32_e32 v0, 4, v0
	s_addc_u32 s9, s87, 0
	v_lshlrev_b32_e32 v48, 4, v2
	v_mov_b32_e32 v49, 0
	v_and_b32_e32 v62, -4, v0
	v_lshl_add_u64 v[0:1], s[86:87], 0, v[48:49]
	s_mov_b64 s[4:5], 0x3200200
	s_add_u32 s10, s86, 0x2200200
	s_mov_b64 s[12:13], 0x1200200
	v_cmp_eq_u32_e64 s[0:1], 0, v213
	v_add_u32_e32 v63, 0xffffc000, v62
	v_lshl_add_u64 v[50:51], v[0:1], 0, s[4:5]
	v_cmp_eq_u32_e64 s[4:5], 0, v2
	s_addc_u32 s11, s87, 0
	v_lshl_add_u64 v[52:53], v[0:1], 0, s[12:13]
	v_lshl_add_u64 v[54:55], s[80:81], 0, v[48:49]
	v_lshl_add_u64 v[56:57], s[78:79], 0, v[48:49]
	s_movk_i32 s29, 0x104
	s_movk_i32 s30, 0x7fff
	s_movk_i32 s31, 0x1000
	s_movk_i32 s34, 0x2000
	s_movk_i32 s35, 0x3000
	v_mov_b32_e32 v64, 1
	v_mbcnt_hi_u32_b32 v65, -1, v212
	s_branch .Lp1a_354

; #define MFMA32(a, b, c) __builtin_amdgcn_mfma_f32_32x32x16_bf16((a), (b), (c), 0, 0, 0)
; DI void hsync() { hsync_impl(false); }
; template <int KSTRIDE, bool WIN, int MASK, int MODE>
; DI void attend_tile(const u16* Ks, const u16* Vts, const bf16x8 (&qf)[4], f32x16 (&O)[2], float& m, float& l, int dbase,
;                     float slope2, bool lanesel, float invl, unsigned* imp_row, int mbase, int lr, int hh) {
;   f32x16 s[2];
; #pragma unroll
;   for (int kt = 0; kt < 2; ++kt) {
; #pragma unroll
;     for (int e = 0; e < 16; ++e) s[kt][e] = 0.f;
; #pragma unroll
;     for (int ks = 0; ks < 4; ++ks) {
;       bf16x8 a = *(const bf16x8*)(Ks + (kt * 32 + lr) * 72 + ks * 16 + hh * 8);
;       s[kt] = MFMA32(a, qf[ks], s[kt]);
;     }
;   }
;   const float fd0 = (float)(dbase - KSTRIDE * 4 * hh);
;   const float ct = slope2 * fd0;
;   float mx = -1e30f;
; #pragma unroll
;   for (int kt = 0; kt < 2; ++kt)
; #pragma unroll
;     for (int e = 0; e < 16; ++e) {
;       const float Ke = (float)(KSTRIDE * (kt * 32 + (e & 3) + 8 * (e >> 2)));
;       float v = fmaf(slope2, Ke, s[kt][e]);
;       if (MASK == 1) {
;         const float fd = fd0 - Ke;
;         bool valid = fd >= 0.f;
;         if (WIN) valid = valid && (fd < 512.f);
;         valid = valid && lanesel;
;         v = valid ? v : -1e30f;
;       }
;       s[kt][e] = v;
;       mx = fmaxf(mx, v);
;     }
;   mx = (mx > -1e29f) ? mx - ct : -1e30f;
;   mx = fmaxf(mx, __shfl_xor(mx, 32));
;   if (MASK == 2) mx = lanesel ? mx : -1e30f;
; DI void kv_commit(const KVRegs& r, u16* Ks, u16* Vts, int tid) {
; #pragma unroll
;   for (int i = 0; i < 2; ++i) {
;     int c = tid + 256 * i;
;     int row = c >> 3, ch = (c & 7) * 8;
;     *(u32x4*)(Ks + row * 72 + ch) = r.k[i];
;     *(u32x4*)(Vts + row * 72 + ch) = r.v[i];
;   }
;   hsync();
.LBB0_547:
	s_mul_i32 s0, s79, 0x4800
	s_add_i32 s81, s33, s0
	v_lshl_add_u32 v0, v100, 1, s81
	v_lshl_add_u32 v1, v158, 1, v0
	v_lshl_add_u32 v0, v159, 1, v0
	s_waitcnt vmcnt(3)
	ds_write_b128 v1, v[80:83]
	s_waitcnt vmcnt(1)
	ds_write_b128 v1, v[84:87] offset:9216
	ds_write_b128 v0, v[88:91]
	s_waitcnt vmcnt(0)
	ds_write_b128 v0, v[92:95] offset:9216
	s_waitcnt vmcnt(0) lgkmcnt(0)
	v_add_u32_e32 v251, 1, v251
	ds_write_b32 v249, v251
.Lfhs_3:
	ds_read_b128 v[244:247], v250
	s_waitcnt lgkmcnt(0)
	v_min3_u32 v248, v244, v245, v246
	v_min_u32_e32 v248, v248, v247
	v_cmp_ge_u32_e32 vcc, v248, v251
	s_cbranch_vccz .Lfhs_3
	s_waitcnt vmcnt(0) lgkmcnt(0)
	v_add3_u32 v38, s81, v161, v162
	ds_read_b128 v[0:3], v38
	ds_read_b128 v[4:7], v38 offset:32
	s_add_i32 s10, s80, 1
	s_lshl_b32 s0, s10, 6
	s_waitcnt lgkmcnt(1)
	v_mfma_f32_32x32x16_bf16 v[16:31], v[0:3], v[64:67], 0
	ds_read_b128 v[0:3], v38 offset:64
	ds_read_b128 v[34:37], v38 offset:4640
	s_cmp_lt_u32 s80, s86
	s_cselect_b32 s0, s0, 0
	s_lshl_b32 s11, s80, 10
	s_add_i32 s8, s0, s88
	s_mov_b32 s9, s18
	s_waitcnt lgkmcnt(2)
	v_mfma_f32_32x32x16_bf16 v[16:31], v[4:7], v[68:71], v[16:31]
	s_lshl_b64 s[8:9], s[8:9], 7
	s_mov_b32 s1, s18
	s_xor_b32 s79, s79, 1
	s_cmp_eq_u32 s80, s86
	s_waitcnt lgkmcnt(1)
	v_mfma_f32_32x32x16_bf16 v[16:31], v[0:3], v[72:75], v[16:31]
	ds_read_b128 v[0:3], v38 offset:96
	s_waitcnt lgkmcnt(0)
	v_mfma_f32_32x32x16_bf16 v[16:31], v[0:3], v[76:79], v[16:31]
	ds_read_b128 v[0:3], v38 offset:4608
	s_waitcnt lgkmcnt(0)
	v_mfma_f32_32x32x16_bf16 v[0:15], v[0:3], v[64:67], 0
	s_nop 8
	v_fma_f32 v16, 0, v106, v16
	v_fmamk_f32 v17, v106, 0x41800000, v17
	v_fmamk_f32 v18, v106, 0x42000000, v18
	v_fmamk_f32 v19, v106, 0x42400000, v19
	v_fmamk_f32 v20, v106, 0x43000000, v20
	v_fmamk_f32 v21, v106, 0x43100000, v21
	v_fmamk_f32 v22, v106, 0x43200000, v22
	v_mfma_f32_32x32x16_bf16 v[0:15], v[34:37], v[68:71], v[0:15]
	ds_read_b128 v[34:37], v38 offset:4672
	v_fmamk_f32 v23, v106, 0x43300000, v23
	v_fmamk_f32 v24, v106, 0x43800000, v24
	v_fmamk_f32 v25, v106, 0x43880000, v25
	v_fmamk_f32 v26, v106, 0x43900000, v26
	v_fmamk_f32 v27, v106, 0x43980000, v27
	v_fmamk_f32 v28, v106, 0x43c00000, v28
	s_waitcnt lgkmcnt(0)
	v_mfma_f32_32x32x16_bf16 v[0:15], v[34:37], v[72:75], v[0:15]
	ds_read_b128 v[34:37], v38 offset:4704
	v_fmamk_f32 v29, v106, 0x43c80000, v29
	v_fmamk_f32 v30, v106, 0x43d00000, v30
	v_fmac_f32_e32 v31, 0x43d80000, v106
	s_waitcnt lgkmcnt(0)
	v_mfma_f32_32x32x16_bf16 v[0:15], v[34:37], v[76:79], v[0:15]
	v_subrev_u32_e32 v34, s11, v135
	v_add_u32_e32 v34, v34, v136
	v_cmp_lt_i32_e32 vcc, -1, v34
	v_cvt_f32_i32_e32 v35, v34
	v_and_b32_e32 v37, 64, v101
	v_cndmask_b32_e32 v16, v160, v16, vcc
	v_cmp_lt_i32_e32 vcc, 15, v34
	s_nop 4
	v_fmamk_f32 v0, v106, 0x44000000, v0
	v_fmamk_f32 v1, v106, 0x44040000, v1
	v_cndmask_b32_e32 v17, v160, v17, vcc
	v_cmp_lt_i32_e32 vcc, 31, v34
	v_max3_f32 v36, v16, s95, v17
	v_fmamk_f32 v2, v106, 0x44080000, v2
	v_cndmask_b32_e32 v18, v160, v18, vcc
	v_cmp_lt_i32_e32 vcc, 47, v34
	v_fmamk_f32 v3, v106, 0x440c0000, v3
	v_fmamk_f32 v4, v106, 0x44200000, v4
	v_cndmask_b32_e32 v19, v160, v19, vcc
	v_cmp_lt_i32_e32 vcc, s96, v34
	v_max3_f32 v36, v36, v18, v19
	v_fmamk_f32 v5, v106, 0x44240000, v5
	v_cndmask_b32_e32 v20, v160, v20, vcc
	v_cmp_lt_i32_e32 vcc, s97, v34
	v_fmamk_f32 v6, v106, 0x44280000, v6
	v_fmamk_f32 v7, v106, 0x442c0000, v7
	v_cndmask_b32_e32 v21, v160, v21, vcc
	v_cmp_lt_i32_e32 vcc, s6, v34
	v_max3_f32 v36, v36, v20, v21
	v_fmamk_f32 v8, v106, 0x44400000, v8
	v_cndmask_b32_e32 v22, v160, v22, vcc
	v_cmp_lt_i32_e32 vcc, s7, v34
	v_fmamk_f32 v9, v106, 0x44440000, v9
	v_fmamk_f32 v10, v106, 0x44480000, v10
	v_cndmask_b32_e32 v23, v160, v23, vcc
	v_cmp_lt_i32_e32 vcc, s34, v34
	v_max3_f32 v36, v36, v22, v23
	v_fmamk_f32 v11, v106, 0x444c0000, v11
	v_cndmask_b32_e32 v24, v160, v24, vcc
	v_cmp_lt_i32_e32 vcc, s35, v34
	v_fmamk_f32 v12, v106, 0x44600000, v12
	v_fmamk_f32 v13, v106, 0x44640000, v13
	v_cndmask_b32_e32 v25, v160, v25, vcc
	v_cmp_lt_i32_e32 vcc, s14, v34
	v_max3_f32 v36, v36, v24, v25
	v_fmamk_f32 v14, v106, 0x44680000, v14
	v_cndmask_b32_e32 v26, v160, v26, vcc
	v_cmp_lt_i32_e32 vcc, s15, v34
	v_fmac_f32_e32 v15, 0x446c0000, v106
	v_add_u32_e32 v131, 64, v37
	v_cndmask_b32_e32 v27, v160, v27, vcc
	v_cmp_lt_i32_e32 vcc, s20, v34
	v_max3_f32 v36, v36, v26, v27
	s_nop 0
	v_cndmask_b32_e32 v28, v160, v28, vcc
	v_cmp_lt_i32_e32 vcc, s21, v34
	s_nop 1
	v_cndmask_b32_e32 v29, v160, v29, vcc
	v_cmp_lt_i32_e32 vcc, s2, v34
	v_max3_f32 v36, v36, v28, v29
	s_nop 0
	v_cndmask_b32_e32 v30, v160, v30, vcc
	v_cmp_lt_i32_e32 vcc, s3, v34
	s_nop 1
	v_cndmask_b32_e32 v31, v160, v31, vcc
	v_cmp_lt_i32_e32 vcc, s24, v34
	v_max3_f32 v36, v36, v30, v31
	s_nop 0
	v_cndmask_b32_e32 v0, v160, v0, vcc
	v_cmp_lt_i32_e32 vcc, s25, v34
	s_nop 1
	v_cndmask_b32_e32 v1, v160, v1, vcc
	v_cmp_lt_i32_e32 vcc, s36, v34
	v_max3_f32 v36, v36, v0, v1
	s_nop 0
	v_cndmask_b32_e32 v2, v160, v2, vcc
	v_cmp_lt_i32_e32 vcc, s37, v34
	s_nop 1
	v_cndmask_b32_e32 v3, v160, v3, vcc
	v_cmp_lt_i32_e32 vcc, s12, v34
	v_max3_f32 v36, v36, v2, v3
	s_nop 0
	v_cndmask_b32_e32 v4, v160, v4, vcc
	v_cmp_lt_i32_e32 vcc, s13, v34
	s_nop 1
	v_cndmask_b32_e32 v5, v160, v5, vcc
	v_cmp_lt_i32_e32 vcc, s22, v34
	v_max3_f32 v36, v36, v4, v5
	s_nop 0
	v_cndmask_b32_e32 v6, v160, v6, vcc
	v_cmp_lt_i32_e32 vcc, s23, v34
	s_nop 1
	v_cndmask_b32_e32 v7, v160, v7, vcc
	v_cmp_lt_i32_e32 vcc, s16, v34
	v_max3_f32 v36, v36, v6, v7
	s_nop 0
	v_cndmask_b32_e32 v8, v160, v8, vcc
	v_cmp_lt_i32_e32 vcc, s17, v34
	s_nop 1
	v_cndmask_b32_e32 v9, v160, v9, vcc
	v_cmp_lt_i32_e32 vcc, s26, v34
	v_max3_f32 v36, v36, v8, v9
	s_nop 0
	v_cndmask_b32_e32 v10, v160, v10, vcc
	v_cmp_lt_i32_e32 vcc, s27, v34
	s_nop 1
	v_cndmask_b32_e32 v11, v160, v11, vcc
	v_cmp_lt_i32_e32 vcc, s28, v34
	v_max3_f32 v36, v36, v10, v11
	s_nop 0
	v_cndmask_b32_e32 v12, v160, v12, vcc
	v_cmp_lt_i32_e32 vcc, s29, v34
	s_nop 1
	v_cndmask_b32_e32 v13, v160, v13, vcc
	v_cmp_lt_i32_e32 vcc, s30, v34
	v_max3_f32 v36, v36, v12, v13
	s_nop 0
	v_cndmask_b32_e32 v14, v160, v14, vcc
	v_cmp_lt_i32_e32 vcc, s31, v34
	s_nop 1
	v_cndmask_b32_e32 v15, v160, v15, vcc
	v_max3_f32 v34, v36, v14, v15
	v_cmp_lt_f32_e32 vcc, s76, v34
	v_fma_f32 v34, -v106, v35, v34
	v_xor_b32_e32 v36, 32, v101
	v_cndmask_b32_e32 v34, v160, v34, vcc
	v_cmp_lt_i32_e32 vcc, v36, v131
	s_nop 1
	v_cndmask_b32_e32 v36, v101, v36, vcc
	v_lshlrev_b32_e32 v163, 2, v36
	ds_bpermute_b32 v36, v163, v34
	v_cmp_lt_f32_e32 vcc, s76, v16
	s_waitcnt lgkmcnt(0)
; DI float fexp2(float x) { return __builtin_amdgcn_exp2f(x); }
; template <int KSTRIDE, bool WIN, int MASK, int MODE>
; DI void attend_tile(const u16* Ks, const u16* Vts, const bf16x8 (&qf)[4], f32x16 (&O)[2], float& m, float& l, int dbase,
;                     float slope2, bool lanesel, float invl, unsigned* imp_row, int mbase, int lr, int hh) {
;     ...
;   float mnew = m, alpha = 1.f;
;   if (MODE != 2) {
;     mnew = fmaxf(m, mx);
;     alpha = fexp2(m - mnew);
;     m = mnew;
;   }
;   float shift = mnew + ct;
;   if (MASK == 2) shift = lanesel ? shift : 1e30f;
;   float rs = 0.f;
; #pragma unroll
;   for (int kt = 0; kt < 2; ++kt)
; #pragma unroll
;     for (int e = 0; e < 16; ++e) {
;       float v = s[kt][e];
;       float pv;
;       if (MASK == 1) pv = (v > -1e29f) ? fexp2(v - shift) : 0.f;
;       else pv = fexp2(v - shift);
;       if (MODE == 2) pv *= invl;
;       s[kt][e] = pv;
;       rs += pv;
;     }
;   if (MODE != 2) l = l * alpha + rs;
;   if (MODE == 1) return;
; DI void attn_item(const Params& p, int item, char* smem) {
;     ...
;     const int cn = (c + 1 < nct) ? c + 1 : 0;
;     kv_issue(kvr, KCMP + ((size_t)(bg * 256 + 64 * cn)) * 64, 64, VCMPT + (size_t)bg * 64 * 256 + 64 * cn, 256, tid);
	v_max3_f32 v137, v33, v34, v36
	v_fma_f32 v34, v106, v35, v137
	v_sub_f32_e32 v16, v16, v34
	v_exp_f32_e32 v16, v16
	s_nop 0
	v_add_f32_e32 v16, 0, v16
	v_cndmask_b32_e32 v16, 0, v16, vcc
	v_cmp_lt_f32_e32 vcc, s76, v17
	v_sub_f32_e32 v17, v17, v34
	v_exp_f32_e32 v17, v17
	s_nop 0
	v_cndmask_b32_e32 v17, 0, v17, vcc
	v_add_f32_e32 v16, v17, v16
	v_sub_f32_e32 v17, v18, v34
	v_exp_f32_e32 v17, v17
	v_cmp_lt_f32_e32 vcc, s76, v18
	s_nop 1
	v_cndmask_b32_e32 v17, 0, v17, vcc
	v_add_f32_e32 v16, v17, v16
	v_sub_f32_e32 v17, v19, v34
	v_exp_f32_e32 v17, v17
	v_cmp_lt_f32_e32 vcc, s76, v19
	s_nop 1
	v_cndmask_b32_e32 v17, 0, v17, vcc
	v_add_f32_e32 v16, v17, v16
	v_sub_f32_e32 v17, v20, v34
	v_exp_f32_e32 v17, v17
	v_cmp_lt_f32_e32 vcc, s76, v20
	s_nop 1
	v_cndmask_b32_e32 v17, 0, v17, vcc
	v_add_f32_e32 v16, v17, v16
	v_sub_f32_e32 v17, v21, v34
	v_exp_f32_e32 v17, v17
	v_cmp_lt_f32_e32 vcc, s76, v21
	s_nop 1
	v_cndmask_b32_e32 v17, 0, v17, vcc
	v_add_f32_e32 v16, v17, v16
	v_sub_f32_e32 v17, v22, v34
	v_exp_f32_e32 v17, v17
	v_cmp_lt_f32_e32 vcc, s76, v22
	s_nop 1
	v_cndmask_b32_e32 v17, 0, v17, vcc
	v_add_f32_e32 v16, v17, v16
	v_sub_f32_e32 v17, v23, v34
	v_exp_f32_e32 v17, v17
	v_cmp_lt_f32_e32 vcc, s76, v23
	s_nop 1
	v_cndmask_b32_e32 v17, 0, v17, vcc
	v_add_f32_e32 v16, v17, v16
	v_sub_f32_e32 v17, v24, v34
	v_exp_f32_e32 v17, v17
	v_cmp_lt_f32_e32 vcc, s76, v24
	s_nop 1
	v_cndmask_b32_e32 v17, 0, v17, vcc
	v_add_f32_e32 v16, v17, v16
	v_sub_f32_e32 v17, v25, v34
	v_exp_f32_e32 v17, v17
	v_cmp_lt_f32_e32 vcc, s76, v25
	s_nop 1
	v_cndmask_b32_e32 v17, 0, v17, vcc
	v_add_f32_e32 v16, v17, v16
	v_sub_f32_e32 v17, v26, v34
	v_exp_f32_e32 v17, v17
	v_cmp_lt_f32_e32 vcc, s76, v26
	s_nop 1
	v_cndmask_b32_e32 v17, 0, v17, vcc
	v_add_f32_e32 v16, v17, v16
	v_sub_f32_e32 v17, v27, v34
	v_exp_f32_e32 v17, v17
	v_cmp_lt_f32_e32 vcc, s76, v27
	s_nop 1
	v_cndmask_b32_e32 v17, 0, v17, vcc
	v_add_f32_e32 v16, v17, v16
	v_sub_f32_e32 v17, v28, v34
	v_exp_f32_e32 v17, v17
	v_cmp_lt_f32_e32 vcc, s76, v28
	s_nop 1
	v_cndmask_b32_e32 v17, 0, v17, vcc
	v_add_f32_e32 v16, v17, v16
	v_sub_f32_e32 v17, v29, v34
	v_exp_f32_e32 v17, v17
	v_cmp_lt_f32_e32 vcc, s76, v29
	s_nop 1
	v_cndmask_b32_e32 v17, 0, v17, vcc
	v_add_f32_e32 v16, v17, v16
	v_sub_f32_e32 v17, v30, v34
	v_exp_f32_e32 v17, v17
	v_cmp_lt_f32_e32 vcc, s76, v30
	s_nop 1
	v_cndmask_b32_e32 v17, 0, v17, vcc
	v_add_f32_e32 v16, v17, v16
	v_sub_f32_e32 v17, v31, v34
	v_exp_f32_e32 v17, v17
	v_cmp_lt_f32_e32 vcc, s76, v31
	s_nop 1
	v_cndmask_b32_e32 v17, 0, v17, vcc
	v_cmp_lt_f32_e32 vcc, s76, v0
	v_sub_f32_e32 v0, v0, v34
	v_exp_f32_e32 v0, v0
	v_add_f32_e32 v16, v17, v16
	v_cndmask_b32_e32 v0, 0, v0, vcc
	v_cmp_lt_f32_e32 vcc, s76, v1
	v_sub_f32_e32 v1, v1, v34
	v_exp_f32_e32 v1, v1
	v_add_f32_e32 v0, v0, v16
	v_cndmask_b32_e32 v1, 0, v1, vcc
	v_add_f32_e32 v0, v1, v0
	v_sub_f32_e32 v1, v2, v34
	v_exp_f32_e32 v1, v1
	v_cmp_lt_f32_e32 vcc, s76, v2
	s_nop 1
	v_cndmask_b32_e32 v1, 0, v1, vcc
	v_add_f32_e32 v0, v1, v0
	v_sub_f32_e32 v1, v3, v34
	v_exp_f32_e32 v1, v1
	v_cmp_lt_f32_e32 vcc, s76, v3
	v_lshl_add_u64 v[2:3], v[122:123], 0, s[8:9]
	s_nop 0
	v_cndmask_b32_e32 v1, 0, v1, vcc
	v_add_f32_e32 v0, v1, v0
	v_sub_f32_e32 v1, v4, v34
	v_exp_f32_e32 v1, v1
	v_cmp_lt_f32_e32 vcc, s76, v4
	s_nop 1
	v_cndmask_b32_e32 v1, 0, v1, vcc
	v_add_f32_e32 v0, v1, v0
	v_cmp_lt_f32_e32 vcc, s76, v5
	v_sub_f32_e32 v1, v5, v34
	v_lshl_add_u64 v[4:5], v[118:119], 1, v[2:3]
	v_lshl_add_u64 v[2:3], v[120:121], 1, v[2:3]
	global_load_dwordx4 v[80:83], v[4:5], off
	global_load_dwordx4 v[88:91], v[2:3], off
	v_lshl_add_u64 v[2:3], s[0:1], 1, v[116:117]
	v_lshl_add_u64 v[4:5], v[108:109], 1, v[2:3]
	v_lshl_add_u64 v[2:3], v[110:111], 1, v[2:3]
	global_load_dwordx4 v[84:87], v[4:5], off
	global_load_dwordx4 v[92:95], v[2:3], off
	v_exp_f32_e32 v1, v1
	s_nop 0
	v_cndmask_b32_e32 v1, 0, v1, vcc
	v_add_f32_e32 v0, v1, v0
	v_sub_f32_e32 v1, v6, v34
	v_exp_f32_e32 v1, v1
	v_cmp_lt_f32_e32 vcc, s76, v6
	s_nop 1
	v_cndmask_b32_e32 v1, 0, v1, vcc
	v_add_f32_e32 v0, v1, v0
	v_sub_f32_e32 v1, v7, v34
	v_exp_f32_e32 v1, v1
	v_cmp_lt_f32_e32 vcc, s76, v7
	s_nop 1
	v_cndmask_b32_e32 v1, 0, v1, vcc
	v_add_f32_e32 v0, v1, v0
	v_sub_f32_e32 v1, v8, v34
	v_exp_f32_e32 v1, v1
	v_cmp_lt_f32_e32 vcc, s76, v8
	s_nop 1
	v_cndmask_b32_e32 v1, 0, v1, vcc
	v_add_f32_e32 v0, v1, v0
	v_sub_f32_e32 v1, v9, v34
	v_exp_f32_e32 v1, v1
	v_cmp_lt_f32_e32 vcc, s76, v9
	s_nop 1
	v_cndmask_b32_e32 v1, 0, v1, vcc
	v_add_f32_e32 v0, v1, v0
	v_sub_f32_e32 v1, v10, v34
	v_exp_f32_e32 v1, v1
	v_cmp_lt_f32_e32 vcc, s76, v10
	s_nop 1
	v_cndmask_b32_e32 v1, 0, v1, vcc
	v_add_f32_e32 v0, v1, v0
	v_sub_f32_e32 v1, v11, v34
	v_exp_f32_e32 v1, v1
	v_cmp_lt_f32_e32 vcc, s76, v11
	s_nop 1
	v_cndmask_b32_e32 v1, 0, v1, vcc
	v_add_f32_e32 v0, v1, v0
	v_sub_f32_e32 v1, v12, v34
	v_exp_f32_e32 v1, v1
	v_cmp_lt_f32_e32 vcc, s76, v12
	s_nop 1
	v_cndmask_b32_e32 v1, 0, v1, vcc
	v_add_f32_e32 v0, v1, v0
	v_sub_f32_e32 v1, v13, v34
	v_exp_f32_e32 v1, v1
	v_cmp_lt_f32_e32 vcc, s76, v13
	s_nop 1
	v_cndmask_b32_e32 v1, 0, v1, vcc
	v_add_f32_e32 v0, v1, v0
	v_sub_f32_e32 v1, v14, v34
	v_exp_f32_e32 v1, v1
	v_cmp_lt_f32_e32 vcc, s76, v14
	s_nop 1
	v_cndmask_b32_e32 v1, 0, v1, vcc
	v_add_f32_e32 v0, v1, v0
	v_sub_f32_e32 v1, v15, v34
	v_exp_f32_e32 v1, v1
	v_cmp_lt_f32_e32 vcc, s76, v15
	s_nop 1
	v_cndmask_b32_e32 v1, 0, v1, vcc
	v_add_f32_e32 v1, v1, v0
	v_sub_f32_e32 v0, v33, v137
	v_exp_f32_e32 v0, v0
	s_nop 0
	v_fmac_f32_e32 v1, v32, v0
	s_cbranch_scc1 .LBB0_558
	v_mov_b32_e32 v32, v1
	s_mov_b32 s80, s10
	v_mov_b32_e32 v33, v137
	s_branch .LBB0_547

; DI void hsync() { hsync_impl(false); }
; DI void kv_commit(const KVRegs& r, u16* Ks, u16* Vts, int tid) {
; #pragma unroll
;   for (int i = 0; i < 2; ++i) {
;     int c = tid + 256 * i;
;     int row = c >> 3, ch = (c & 7) * 8;
;     *(u32x4*)(Ks + row * 72 + ch) = r.k[i];
;     *(u32x4*)(Vts + row * 72 + ch) = r.v[i];
;   }
;   hsync();
; DI void attn_item(const Params& p, int item, char* smem) {
;     ...
;     for (int c = 0; c < nct; ++c) {
;       kv_commit(kvr, Ks, Vts, tid);
;       if (c + 1 < nct) kv_issue(kvr, KCMP + ((size_t)(bg * 256 + 64 * (c + 1))) * 64, 64, VCMPT + (size_t)bg * 64 * 256 + 64 * (c + 1), 256, tid);
.LBB0_559:
	s_mul_i32 s0, s79, 0x4800
	s_add_i32 s81, s33, s0
	v_lshl_add_u32 v32, v100, 1, s81
	v_lshl_add_u32 v33, v158, 1, v32
	v_lshl_add_u32 v32, v159, 1, v32
	s_waitcnt vmcnt(3)
	ds_write_b128 v33, v[80:83]
	s_waitcnt vmcnt(1)
	ds_write_b128 v33, v[84:87] offset:9216
	ds_write_b128 v32, v[88:91]
	s_waitcnt vmcnt(0)
	ds_write_b128 v32, v[92:95] offset:9216
	s_waitcnt vmcnt(0) lgkmcnt(0)
	v_add_u32_e32 v251, 1, v251
	ds_write_b32 v249, v251
.Lfhs_2:
	ds_read_b128 v[244:247], v250
	s_waitcnt lgkmcnt(0)
	v_min3_u32 v248, v244, v245, v246
	v_min_u32_e32 v248, v248, v247
	v_cmp_ge_u32_e32 vcc, v248, v251
	s_cbranch_vccz .Lfhs_2
	s_waitcnt vmcnt(0) lgkmcnt(0)
	s_add_i32 s8, s80, 1
	s_cmp_ge_u32 s80, s86
	s_cbranch_scc1 .LBB0_570
	s_lshl_b32 s0, s8, 6
	s_add_i32 s10, s0, s88
	s_mov_b32 s11, s18
	s_lshl_b64 s[10:11], s[10:11], 7
	s_mov_b32 s1, s18
	v_lshl_add_u64 v[32:33], v[122:123], 0, s[10:11]
	v_lshl_add_u64 v[34:35], s[0:1], 1, v[116:117]
	v_lshl_add_u64 v[36:37], v[118:119], 1, v[32:33]
	v_lshl_add_u64 v[32:33], v[120:121], 1, v[32:33]
	v_lshl_add_u64 v[38:39], v[108:109], 1, v[34:35]
	global_load_dwordx4 v[80:83], v[36:37], off
	global_load_dwordx4 v[84:87], v[38:39], off
	v_lshl_add_u64 v[34:35], v[110:111], 1, v[34:35]
	global_load_dwordx4 v[88:91], v[32:33], off
	global_load_dwordx4 v[92:95], v[34:35], off

; DI void hsync() { hsync_impl(false); }
; DI void kv_commit(const KVRegs& r, u16* Ks, u16* Vts, int tid) {
; #pragma unroll
;   for (int i = 0; i < 2; ++i) {
;     int c = tid + 256 * i;
;     int row = c >> 3, ch = (c & 7) * 8;
;     *(u32x4*)(Ks + row * 72 + ch) = r.k[i];
;     *(u32x4*)(Vts + row * 72 + ch) = r.v[i];
;   }
;   hsync();
; DI void attn_item(const Params& p, int item, char* smem) {
;     ...
;     for (int i = i0; i < 9; ++i) {
;       const int k0 = kbase + 64 * i;
;       kv_commit(kvr, Ks, Vts, tid);
;       if (i + 1 < 9) kv_issue(kvr, KW + ((size_t)(b * 4096 + k0 + 64)) * 128 + g * 64, 128, VTW + (size_t)bg * 64 * 4096 + k0 + 64, 4096, tid);
.LBB0_612:
	s_mul_i32 s0, s79, 0x4800
	s_add_i32 s38, s33, s0
	v_lshl_add_u32 v0, v100, 1, s38
	v_lshl_add_u32 v1, v158, 1, v0
	v_lshl_add_u32 v0, v159, 1, v0
	s_waitcnt vmcnt(0)
	ds_write_b128 v1, v[44:47]
	ds_write_b128 v1, v[36:39] offset:9216
	ds_write_b128 v0, v[40:43]
	ds_write_b128 v0, v[32:35] offset:9216
	s_waitcnt vmcnt(0) lgkmcnt(0)
	v_add_u32_e32 v251, 1, v251
	ds_write_b32 v249, v251
.Lfhs_1:
	ds_read_b128 v[244:247], v250
	s_waitcnt lgkmcnt(0)
	v_min3_u32 v248, v244, v245, v246
	v_min_u32_e32 v248, v248, v247
	v_cmp_ge_u32_e32 vcc, v248, v251
	s_cbranch_vccz .Lfhs_1
	s_lshl_b32 s0, s89, 6
	s_waitcnt vmcnt(0) lgkmcnt(0)
	s_add_i32 s8, s0, s88
	s_cmp_eq_u32 s89, 8
	s_cbranch_scc1 .LBB0_623
	s_add_i32 s10, s90, s8
	s_ashr_i32 s11, s10, 31
	s_lshl_b64 s[10:11], s[10:11], 8
	v_lshl_add_u64 v[0:1], v[92:93], 0, s[10:11]
	s_lshl_b32 s0, s0, 1
	s_mov_b32 s1, s18
	v_lshl_add_u64 v[2:3], v[94:95], 0, s[0:1]
	v_lshl_add_u64 v[4:5], v[102:103], 1, v[0:1]
	v_lshl_add_u64 v[0:1], v[104:105], 1, v[0:1]
	v_lshl_add_u64 v[6:7], v[88:89], 1, v[2:3]
	global_load_dwordx4 v[44:47], v[4:5], off
	global_load_dwordx4 v[36:39], v[6:7], off offset:-896
	v_lshl_add_u64 v[2:3], v[90:91], 1, v[2:3]
	global_load_dwordx4 v[40:43], v[0:1], off
	global_load_dwordx4 v[32:35], v[2:3], off offset:-896

; DI void hsync() { hsync_impl(false); }
; DI void kv_commit(const KVRegs& r, u16* Ks, u16* Vts, int tid) {
; #pragma unroll
;   for (int i = 0; i < 2; ++i) {
;     int c = tid + 256 * i;
;     int row = c >> 3, ch = (c & 7) * 8;
;     *(u32x4*)(Ks + row * 72 + ch) = r.k[i];
;     *(u32x4*)(Vts + row * 72 + ch) = r.v[i];
;   }
;   hsync();
; DI void attn_item(const Params& p, int item, char* smem) {
;     ...
;     while (j >= 0) {
;       kv_commit(kvr, Ks, Vts, tid);
;       int jn = -1;
;       if (am) { jn = __builtin_ctzll(am); am &= am - 1; }
;       if (jn >= 0) kv_issue(kvr, KS + ((size_t)(b * 4096 + 64 * jn)) * 128 + g * 64, 128, VTS + (size_t)bg * 64 * 4096 + 64 * jn, 4096, tid);
.LBB0_631:
	s_mul_i32 s0, s79, 0x4800
	s_add_i32 s81, s33, s0
	v_lshl_add_u32 v0, v100, 1, s81
	v_lshl_add_u32 v1, v158, 1, v0
	v_lshl_add_u32 v0, v159, 1, v0
	s_waitcnt vmcnt(3)
	ds_write_b128 v1, v[80:83]
	s_waitcnt vmcnt(2)
	ds_write_b128 v1, v[84:87] offset:9216
	s_waitcnt vmcnt(1)
	ds_write_b128 v0, v[88:91]
	s_waitcnt vmcnt(0)
	ds_write_b128 v0, v[92:95] offset:9216
	s_waitcnt vmcnt(0) lgkmcnt(0)
	v_add_u32_e32 v251, 1, v251
	ds_write_b32 v249, v251
.Lfhs_0:
	ds_read_b128 v[244:247], v250
	s_waitcnt lgkmcnt(0)
	v_min3_u32 v248, v244, v245, v246
	v_min_u32_e32 v248, v248, v247
	v_cmp_ge_u32_e32 vcc, v248, v251
	s_cbranch_vccz .Lfhs_0
	s_ff1_i32_b64 s92, s[88:89]
	s_cmp_lg_u64 s[88:89], 0
	s_cselect_b32 s0, s92, -1
	s_waitcnt vmcnt(0) lgkmcnt(0)
	s_cmp_lt_i32 s0, 0
	s_cselect_b64 s[90:91], -1, 0
	s_and_b64 vcc, exec, s[90:91]
	s_cbranch_vccnz .LBB0_642
	s_lshl_b32 s1, s0, 6
	s_add_i32 vcc_lo, s1, s38
	s_mov_b32 vcc_hi, s18
	s_lshl_b64 vcc, vcc, 8
	v_lshl_add_u64 v[0:1], v[118:119], 0, vcc
	s_lshl_b32 s0, s0, 7
	s_mov_b32 s1, s18
	v_lshl_add_u64 v[2:3], v[120:121], 0, s[0:1]
	v_lshl_add_u64 v[4:5], v[0:1], 0, v[108:109]
	v_lshl_add_u64 v[0:1], v[0:1], 0, v[110:111]
	v_lshl_add_u64 v[6:7], v[2:3], 0, v[58:59]
	global_load_dwordx4 v[80:83], v[4:5], off
	global_load_dwordx4 v[84:87], v[6:7], off
	v_lshl_add_u64 v[2:3], v[2:3], 0, v[60:61]
	global_load_dwordx4 v[88:91], v[0:1], off
	global_load_dwordx4 v[92:95], v[2:3], off
